# NSA top-k rank computation rewritten as 64-bit unique-key compare with carry-add (exact), on top of stage-2 de-serialisation
# speedup vs baseline: 1.0086x; 1.0086x over previous
; __device__ __forceinline__ void nsa_tile(const Params& p, int qb, int bg, char* smem) {
;     ...
;             float v = (part[(0 * 32 + tok) * 64 + lane] + part[(1 * 32 + tok) * 64 + lane]) + (part[(2 * 32 + tok) * 64 + lane] + part[(3 * 32 + tok) * 64 + lane]);
;             v = (lane < 8 * ((qb >> 4) + 1)) ? v : 0.f;
;             const bool forced = (lane == 0) || (lane == cur) || (lane == cur - 1);
;             const bool future = lane > cur;
;             v = forced ? 1e9f : (future ? -1e9f : v);
;             int cnt = 0;
; #pragma unroll
;             for (int i = 0; i < 64; ++i) {
;                 const float vi = __uint_as_float(__builtin_amdgcn_readlane(__float_as_uint(v), i));
;                 cnt += ((vi > v) || (vi == v && i < lane)) ? 1 : 0;
;             }
;             const u64 mk = __ballot((cnt < 16) && !future);
;             if (lane == 0) selmask[tok] = mk;
.LBB0_357:
	v_ashrrev_i32_e32 v56, 6, v55
	v_cmp_lt_i32_e32 vcc, 15, v56
	s_mov_b64 s[2:3], 0
	s_and_saveexec_b64 s[42:43], vcc
	s_xor_b64 s[44:45], exec, s[42:43]
	s_cbranch_execz .LBB0_360
	ds_read2st64_b32 v[52:53], v54 offset1:32
	ds_read2st64_b32 v[58:59], v54 offset0:64 offset1:96
	v_readlane_b32 s2, v244, 19
	v_readlane_b32 s3, v244, 20
	v_cmp_eq_u32_e32 vcc, v78, v56
	s_waitcnt lgkmcnt(1)
	v_mov_b32_e32 v60, v52
	s_waitcnt lgkmcnt(0)
	v_mov_b32_e32 v61, v58
	v_mov_b32_e32 v58, v53
	v_pk_add_f32 v[52:53], v[60:61], v[58:59]
	v_cmp_le_i32_e64 s[42:43], v78, v56
	v_add_f32_e32 v52, v52, v53
	v_add_u32_e32 v53, -1, v56
	v_cndmask_b32_e64 v52, 0, v52, s[2:3]
	s_or_b64 s[2:3], s[4:5], vcc
	v_cmp_eq_u32_e32 vcc, v78, v53
	s_or_b64 vcc, s[2:3], vcc
	v_cndmask_b32_e64 v52, v109, v52, s[42:43]
	v_cndmask_b32_e32 v52, v52, v110, vcc
	v_readfirstlane_b32 s46, v56
	v_ashrrev_i32_e32 v53, 31, v52
	v_or_b32_e32 v53, 0x80000000, v53
	v_xor_b32_e32 v247, v52, v53
	v_sub_u32_e32 v246, 63, v78
	v_mov_b32_e32 v52, 0
	s_cmp_lt_u32 s46, 32
	s_cbranch_scc1 .Ltk_c31
	s_cmp_lt_u32 s46, 48
	s_cbranch_scc1 .Ltk_c47
	v_readlane_b32 s3, v247, 63
	v_readlane_b32 s47, v247, 62
	s_movk_i32 s2, 0
	s_movk_i32 s46, 1
	v_cmp_gt_u64_e32 vcc, s[2:3], v[246:247]
	v_cmp_gt_u64_e64 s[98:99], s[46:47], v[246:247]
	v_readlane_b32 s3, v247, 61
	v_readlane_b32 s47, v247, 60
	v_addc_co_u32_e32 v52, vcc, 0, v52, vcc
	v_addc_co_u32_e64 v52, s[100:101], 0, v52, s[98:99]
	s_movk_i32 s2, 2
	s_movk_i32 s46, 3
	v_cmp_gt_u64_e32 vcc, s[2:3], v[246:247]
	v_cmp_gt_u64_e64 s[98:99], s[46:47], v[246:247]
	v_readlane_b32 s3, v247, 59
	v_readlane_b32 s47, v247, 58
	v_addc_co_u32_e32 v52, vcc, 0, v52, vcc
	v_addc_co_u32_e64 v52, s[100:101], 0, v52, s[98:99]
	s_movk_i32 s2, 4
	s_movk_i32 s46, 5
	v_cmp_gt_u64_e32 vcc, s[2:3], v[246:247]
	v_cmp_gt_u64_e64 s[98:99], s[46:47], v[246:247]
	v_readlane_b32 s3, v247, 57
	v_readlane_b32 s47, v247, 56
	v_addc_co_u32_e32 v52, vcc, 0, v52, vcc
	v_addc_co_u32_e64 v52, s[100:101], 0, v52, s[98:99]
	s_movk_i32 s2, 6
	s_movk_i32 s46, 7
	v_cmp_gt_u64_e32 vcc, s[2:3], v[246:247]
	v_cmp_gt_u64_e64 s[98:99], s[46:47], v[246:247]
	v_readlane_b32 s3, v247, 55
	v_readlane_b32 s47, v247, 54
	v_addc_co_u32_e32 v52, vcc, 0, v52, vcc
	v_addc_co_u32_e64 v52, s[100:101], 0, v52, s[98:99]
	s_movk_i32 s2, 8
	s_movk_i32 s46, 9
	v_cmp_gt_u64_e32 vcc, s[2:3], v[246:247]
	v_cmp_gt_u64_e64 s[98:99], s[46:47], v[246:247]
	v_readlane_b32 s3, v247, 53
	v_readlane_b32 s47, v247, 52
	v_addc_co_u32_e32 v52, vcc, 0, v52, vcc
	v_addc_co_u32_e64 v52, s[100:101], 0, v52, s[98:99]
	s_movk_i32 s2, 10
	s_movk_i32 s46, 11
	v_cmp_gt_u64_e32 vcc, s[2:3], v[246:247]
	v_cmp_gt_u64_e64 s[98:99], s[46:47], v[246:247]
	v_readlane_b32 s3, v247, 51
	v_readlane_b32 s47, v247, 50
	v_addc_co_u32_e32 v52, vcc, 0, v52, vcc
	v_addc_co_u32_e64 v52, s[100:101], 0, v52, s[98:99]
	s_movk_i32 s2, 12
	s_movk_i32 s46, 13
	v_cmp_gt_u64_e32 vcc, s[2:3], v[246:247]
	v_cmp_gt_u64_e64 s[98:99], s[46:47], v[246:247]
	v_readlane_b32 s3, v247, 49
	v_readlane_b32 s47, v247, 48
	v_addc_co_u32_e32 v52, vcc, 0, v52, vcc
	v_addc_co_u32_e64 v52, s[100:101], 0, v52, s[98:99]
	s_movk_i32 s2, 14
	s_movk_i32 s46, 15
	v_cmp_gt_u64_e32 vcc, s[2:3], v[246:247]
	v_cmp_gt_u64_e64 s[98:99], s[46:47], v[246:247]
	s_nop 1
	v_addc_co_u32_e32 v52, vcc, 0, v52, vcc
	v_addc_co_u32_e64 v52, s[100:101], 0, v52, s[98:99]
.Ltk_c47:
	v_readlane_b32 s3, v247, 47
	v_readlane_b32 s47, v247, 46
	s_movk_i32 s2, 16
	s_movk_i32 s46, 17
	v_cmp_gt_u64_e32 vcc, s[2:3], v[246:247]
	v_cmp_gt_u64_e64 s[98:99], s[46:47], v[246:247]
	v_readlane_b32 s3, v247, 45
	v_readlane_b32 s47, v247, 44
	v_addc_co_u32_e32 v52, vcc, 0, v52, vcc
	v_addc_co_u32_e64 v52, s[100:101], 0, v52, s[98:99]
	s_movk_i32 s2, 18
	s_movk_i32 s46, 19
	v_cmp_gt_u64_e32 vcc, s[2:3], v[246:247]
	v_cmp_gt_u64_e64 s[98:99], s[46:47], v[246:247]
	v_readlane_b32 s3, v247, 43
	v_readlane_b32 s47, v247, 42
	v_addc_co_u32_e32 v52, vcc, 0, v52, vcc
	v_addc_co_u32_e64 v52, s[100:101], 0, v52, s[98:99]
	s_movk_i32 s2, 20
	s_movk_i32 s46, 21
	v_cmp_gt_u64_e32 vcc, s[2:3], v[246:247]
	v_cmp_gt_u64_e64 s[98:99], s[46:47], v[246:247]
	v_readlane_b32 s3, v247, 41
	v_readlane_b32 s47, v247, 40
	v_addc_co_u32_e32 v52, vcc, 0, v52, vcc
	v_addc_co_u32_e64 v52, s[100:101], 0, v52, s[98:99]
	s_movk_i32 s2, 22
	s_movk_i32 s46, 23
	v_cmp_gt_u64_e32 vcc, s[2:3], v[246:247]
	v_cmp_gt_u64_e64 s[98:99], s[46:47], v[246:247]
	v_readlane_b32 s3, v247, 39
	v_readlane_b32 s47, v247, 38
	v_addc_co_u32_e32 v52, vcc, 0, v52, vcc
	v_addc_co_u32_e64 v52, s[100:101], 0, v52, s[98:99]
	s_movk_i32 s2, 24
	s_movk_i32 s46, 25
	v_cmp_gt_u64_e32 vcc, s[2:3], v[246:247]
	v_cmp_gt_u64_e64 s[98:99], s[46:47], v[246:247]
	v_readlane_b32 s3, v247, 37
	v_readlane_b32 s47, v247, 36
	v_addc_co_u32_e32 v52, vcc, 0, v52, vcc
	v_addc_co_u32_e64 v52, s[100:101], 0, v52, s[98:99]
	s_movk_i32 s2, 26
	s_movk_i32 s46, 27
	v_cmp_gt_u64_e32 vcc, s[2:3], v[246:247]
	v_cmp_gt_u64_e64 s[98:99], s[46:47], v[246:247]
	v_readlane_b32 s3, v247, 35
	v_readlane_b32 s47, v247, 34
	v_addc_co_u32_e32 v52, vcc, 0, v52, vcc
	v_addc_co_u32_e64 v52, s[100:101], 0, v52, s[98:99]
	s_movk_i32 s2, 28
	s_movk_i32 s46, 29
	v_cmp_gt_u64_e32 vcc, s[2:3], v[246:247]
	v_cmp_gt_u64_e64 s[98:99], s[46:47], v[246:247]
	v_readlane_b32 s3, v247, 33
	v_readlane_b32 s47, v247, 32
	v_addc_co_u32_e32 v52, vcc, 0, v52, vcc
	v_addc_co_u32_e64 v52, s[100:101], 0, v52, s[98:99]
	s_movk_i32 s2, 30
	s_movk_i32 s46, 31
	v_cmp_gt_u64_e32 vcc, s[2:3], v[246:247]
	v_cmp_gt_u64_e64 s[98:99], s[46:47], v[246:247]
	s_nop 1
	v_addc_co_u32_e32 v52, vcc, 0, v52, vcc
	v_addc_co_u32_e64 v52, s[100:101], 0, v52, s[98:99]
; __device__ __forceinline__ void nsa_tile(const Params& p, int qb, int bg, char* smem) {
;     ...
;             int cnt = 0;
; #pragma unroll
;             for (int i = 0; i < 64; ++i) {
;                 const float vi = __uint_as_float(__builtin_amdgcn_readlane(__float_as_uint(v), i));
;                 cnt += ((vi > v) || (vi == v && i < lane)) ? 1 : 0;
;             }
;             const u64 mk = __ballot((cnt < 16) && !future);
;             if (lane == 0) selmask[tok] = mk;
.Ltk_c31:
	v_readlane_b32 s3, v247, 31
	v_readlane_b32 s47, v247, 30
	s_movk_i32 s2, 32
	s_movk_i32 s46, 33
	v_cmp_gt_u64_e32 vcc, s[2:3], v[246:247]
	v_cmp_gt_u64_e64 s[98:99], s[46:47], v[246:247]
	v_readlane_b32 s3, v247, 29
	v_readlane_b32 s47, v247, 28
	v_addc_co_u32_e32 v52, vcc, 0, v52, vcc
	v_addc_co_u32_e64 v52, s[100:101], 0, v52, s[98:99]
	s_movk_i32 s2, 34
	s_movk_i32 s46, 35
	v_cmp_gt_u64_e32 vcc, s[2:3], v[246:247]
	v_cmp_gt_u64_e64 s[98:99], s[46:47], v[246:247]
	v_readlane_b32 s3, v247, 27
	v_readlane_b32 s47, v247, 26
	v_addc_co_u32_e32 v52, vcc, 0, v52, vcc
	v_addc_co_u32_e64 v52, s[100:101], 0, v52, s[98:99]
	s_movk_i32 s2, 36
	s_movk_i32 s46, 37
	v_cmp_gt_u64_e32 vcc, s[2:3], v[246:247]
	v_cmp_gt_u64_e64 s[98:99], s[46:47], v[246:247]
	v_readlane_b32 s3, v247, 25
	v_readlane_b32 s47, v247, 24
	v_addc_co_u32_e32 v52, vcc, 0, v52, vcc
	v_addc_co_u32_e64 v52, s[100:101], 0, v52, s[98:99]
	s_movk_i32 s2, 38
	s_movk_i32 s46, 39
	v_cmp_gt_u64_e32 vcc, s[2:3], v[246:247]
	v_cmp_gt_u64_e64 s[98:99], s[46:47], v[246:247]
	v_readlane_b32 s3, v247, 23
	v_readlane_b32 s47, v247, 22
	v_addc_co_u32_e32 v52, vcc, 0, v52, vcc
	v_addc_co_u32_e64 v52, s[100:101], 0, v52, s[98:99]
	s_movk_i32 s2, 40
	s_movk_i32 s46, 41
	v_cmp_gt_u64_e32 vcc, s[2:3], v[246:247]
	v_cmp_gt_u64_e64 s[98:99], s[46:47], v[246:247]
	v_readlane_b32 s3, v247, 21
	v_readlane_b32 s47, v247, 20
	v_addc_co_u32_e32 v52, vcc, 0, v52, vcc
	v_addc_co_u32_e64 v52, s[100:101], 0, v52, s[98:99]
	s_movk_i32 s2, 42
	s_movk_i32 s46, 43
	v_cmp_gt_u64_e32 vcc, s[2:3], v[246:247]
	v_cmp_gt_u64_e64 s[98:99], s[46:47], v[246:247]
	v_readlane_b32 s3, v247, 19
	v_readlane_b32 s47, v247, 18
	v_addc_co_u32_e32 v52, vcc, 0, v52, vcc
	v_addc_co_u32_e64 v52, s[100:101], 0, v52, s[98:99]
	s_movk_i32 s2, 44
	s_movk_i32 s46, 45
	v_cmp_gt_u64_e32 vcc, s[2:3], v[246:247]
	v_cmp_gt_u64_e64 s[98:99], s[46:47], v[246:247]
	v_readlane_b32 s3, v247, 17
	v_readlane_b32 s47, v247, 16
	v_addc_co_u32_e32 v52, vcc, 0, v52, vcc
	v_addc_co_u32_e64 v52, s[100:101], 0, v52, s[98:99]
	s_movk_i32 s2, 46
	s_movk_i32 s46, 47
	v_cmp_gt_u64_e32 vcc, s[2:3], v[246:247]
	v_cmp_gt_u64_e64 s[98:99], s[46:47], v[246:247]
	v_readlane_b32 s3, v247, 15
	v_readlane_b32 s47, v247, 14
	v_addc_co_u32_e32 v52, vcc, 0, v52, vcc
	v_addc_co_u32_e64 v52, s[100:101], 0, v52, s[98:99]
	s_movk_i32 s2, 48
	s_movk_i32 s46, 49
	v_cmp_gt_u64_e32 vcc, s[2:3], v[246:247]
	v_cmp_gt_u64_e64 s[98:99], s[46:47], v[246:247]
	v_readlane_b32 s3, v247, 13
	v_readlane_b32 s47, v247, 12
	v_addc_co_u32_e32 v52, vcc, 0, v52, vcc
	v_addc_co_u32_e64 v52, s[100:101], 0, v52, s[98:99]
	s_movk_i32 s2, 50
	s_movk_i32 s46, 51
	v_cmp_gt_u64_e32 vcc, s[2:3], v[246:247]
	v_cmp_gt_u64_e64 s[98:99], s[46:47], v[246:247]
	v_readlane_b32 s3, v247, 11
	v_readlane_b32 s47, v247, 10
	v_addc_co_u32_e32 v52, vcc, 0, v52, vcc
	v_addc_co_u32_e64 v52, s[100:101], 0, v52, s[98:99]
	s_movk_i32 s2, 52
	s_movk_i32 s46, 53
	v_cmp_gt_u64_e32 vcc, s[2:3], v[246:247]
	v_cmp_gt_u64_e64 s[98:99], s[46:47], v[246:247]
	v_readlane_b32 s3, v247, 9
	v_readlane_b32 s47, v247, 8
	v_addc_co_u32_e32 v52, vcc, 0, v52, vcc
	v_addc_co_u32_e64 v52, s[100:101], 0, v52, s[98:99]
	s_movk_i32 s2, 54
	s_movk_i32 s46, 55
	v_cmp_gt_u64_e32 vcc, s[2:3], v[246:247]
	v_cmp_gt_u64_e64 s[98:99], s[46:47], v[246:247]
	v_readlane_b32 s3, v247, 7
	v_readlane_b32 s47, v247, 6
	v_addc_co_u32_e32 v52, vcc, 0, v52, vcc
	v_addc_co_u32_e64 v52, s[100:101], 0, v52, s[98:99]
	s_movk_i32 s2, 56
	s_movk_i32 s46, 57
	v_cmp_gt_u64_e32 vcc, s[2:3], v[246:247]
	v_cmp_gt_u64_e64 s[98:99], s[46:47], v[246:247]
	v_readlane_b32 s3, v247, 5
	v_readlane_b32 s47, v247, 4
	v_addc_co_u32_e32 v52, vcc, 0, v52, vcc
	v_addc_co_u32_e64 v52, s[100:101], 0, v52, s[98:99]
	s_movk_i32 s2, 58
	s_movk_i32 s46, 59
	v_cmp_gt_u64_e32 vcc, s[2:3], v[246:247]
	v_cmp_gt_u64_e64 s[98:99], s[46:47], v[246:247]
	v_readlane_b32 s3, v247, 3
	v_readlane_b32 s47, v247, 2
	v_addc_co_u32_e32 v52, vcc, 0, v52, vcc
	v_addc_co_u32_e64 v52, s[100:101], 0, v52, s[98:99]
	s_movk_i32 s2, 60
	s_movk_i32 s46, 61
	v_cmp_gt_u64_e32 vcc, s[2:3], v[246:247]
	v_cmp_gt_u64_e64 s[98:99], s[46:47], v[246:247]
	v_readlane_b32 s3, v247, 1
	v_readlane_b32 s47, v247, 0
	v_addc_co_u32_e32 v52, vcc, 0, v52, vcc
	v_addc_co_u32_e64 v52, s[100:101], 0, v52, s[98:99]
	s_movk_i32 s2, 62
	s_movk_i32 s46, 63
	v_cmp_gt_u64_e32 vcc, s[2:3], v[246:247]
	v_cmp_gt_u64_e64 s[98:99], s[46:47], v[246:247]
	s_nop 1
	v_addc_co_u32_e32 v52, vcc, 0, v52, vcc
	v_addc_co_u32_e64 v52, s[100:101], 0, v52, s[98:99]
	v_cmp_gt_u32_e32 vcc, 16, v52
	s_and_b64 s[2:3], s[42:43], vcc
	v_cndmask_b32_e64 v52, 0, 1, s[2:3]
	v_cmp_ne_u32_e64 s[46:47], 0, v52
	s_and_b64 s[2:3], s[4:5], exec
	s_or_saveexec_b64 s[42:43], s[44:45]
	v_mov_b64_e32 v[52:53], s[46:47]
	s_xor_b64 exec, exec, s[42:43]
	s_cbranch_execnz .LBB0_361
